# select search: one of every four compare/add-carry pairs goes through VCC with the short VOPC/VOP2 encodings; per-pass trims
# speedup vs baseline: 1.0047x; 1.0021x over previous
; __device__ __forceinline__ int count_ge(const unsigned (&u)[64], unsigned cand, int nblk) {
;     int c0 = 0, c1 = 0;
;     const unsigned ts = __builtin_amdgcn_readfirstlane(cand);
; #pragma unroll
;     for (int B = 0; B < 2; ++B) {
;         if (B < nblk) {
; #pragma unroll
;             for (int i = 0; i < 32; i += 4) CNT4(c0, c1, ts, u[B * 32 + i], u[B * 32 + i + 1], u[B * 32 + i + 2], u[B * 32 + i + 3]);
;         }
;     }
;     return wave_isum(c0 + c1);
; }
.Lsqa_count:
	v_cmp_le_u32_e32 vcc, s14, v138
	v_cmp_le_u32_e64 s[6:7], s14, v140
	v_cmp_le_u32_e64 s[10:11], s14, v139
	v_cmp_le_u32_e64 s[26:27], s14, v141
	v_addc_co_u32_e64 v0, vcc, 0, 0, vcc
	v_addc_co_u32_e64 v34, s[30:31], 0, 0, s[6:7]
	v_addc_co_u32_e64 v0, s[28:29], 0, v0, s[10:11]
	v_addc_co_u32_e64 v34, s[30:31], 0, v34, s[26:27]
	v_cmp_le_u32_e32 vcc, s14, v142
	v_cmp_le_u32_e64 s[6:7], s14, v146
	v_cmp_le_u32_e64 s[10:11], s14, v143
	v_cmp_le_u32_e64 s[26:27], s14, v147
	v_addc_co_u32_e32 v0, vcc, 0, v0, vcc
	v_addc_co_u32_e64 v34, s[30:31], 0, v34, s[6:7]
	v_addc_co_u32_e64 v0, s[28:29], 0, v0, s[10:11]
	v_addc_co_u32_e64 v34, s[30:31], 0, v34, s[26:27]
	s_cmp_eq_u32 s32, 1
	s_cbranch_scc1 .Lsqa_red
	v_cmp_le_u32_e32 vcc, s14, v144
	v_cmp_le_u32_e64 s[6:7], s14, v148
	v_cmp_le_u32_e64 s[10:11], s14, v145
	v_cmp_le_u32_e64 s[26:27], s14, v149
	v_addc_co_u32_e32 v0, vcc, 0, v0, vcc
	v_addc_co_u32_e64 v34, s[30:31], 0, v34, s[6:7]
	v_addc_co_u32_e64 v0, s[28:29], 0, v0, s[10:11]
	v_addc_co_u32_e64 v34, s[30:31], 0, v34, s[26:27]
	v_cmp_le_u32_e32 vcc, s14, v150
	v_cmp_le_u32_e64 s[6:7], s14, v152
	v_cmp_le_u32_e64 s[10:11], s14, v151
	v_cmp_le_u32_e64 s[26:27], s14, v154
	v_addc_co_u32_e32 v0, vcc, 0, v0, vcc
	v_addc_co_u32_e64 v34, s[30:31], 0, v34, s[6:7]
	v_addc_co_u32_e64 v0, s[28:29], 0, v0, s[10:11]
	v_addc_co_u32_e64 v34, s[30:31], 0, v34, s[26:27]
	s_cmp_eq_u32 s32, 2
	s_cbranch_scc1 .Lsqa_red
	v_cmp_le_u32_e32 vcc, s14, v153
	v_cmp_le_u32_e64 s[6:7], s14, v156
	v_cmp_le_u32_e64 s[10:11], s14, v155
	v_cmp_le_u32_e64 s[26:27], s14, v157
	v_addc_co_u32_e32 v0, vcc, 0, v0, vcc
	v_addc_co_u32_e64 v34, s[30:31], 0, v34, s[6:7]
	v_addc_co_u32_e64 v0, s[28:29], 0, v0, s[10:11]
	v_addc_co_u32_e64 v34, s[30:31], 0, v34, s[26:27]
	v_cmp_le_u32_e32 vcc, s14, v158
	v_cmp_le_u32_e64 s[6:7], s14, v160
	v_cmp_le_u32_e64 s[10:11], s14, v159
	v_cmp_le_u32_e64 s[26:27], s14, v161
	v_addc_co_u32_e32 v0, vcc, 0, v0, vcc
	v_addc_co_u32_e64 v34, s[30:31], 0, v34, s[6:7]
	v_addc_co_u32_e64 v0, s[28:29], 0, v0, s[10:11]
	v_addc_co_u32_e64 v34, s[30:31], 0, v34, s[26:27]
	v_cmp_le_u32_e32 vcc, s14, v167
	v_cmp_le_u32_e64 s[6:7], s14, v169
	v_cmp_le_u32_e64 s[10:11], s14, v168
	v_cmp_le_u32_e64 s[26:27], s14, v170
	v_addc_co_u32_e32 v0, vcc, 0, v0, vcc
	v_addc_co_u32_e64 v34, s[30:31], 0, v34, s[6:7]
	v_addc_co_u32_e64 v0, s[28:29], 0, v0, s[10:11]
	v_addc_co_u32_e64 v34, s[30:31], 0, v34, s[26:27]
	v_cmp_le_u32_e32 vcc, s14, v173
	v_cmp_le_u32_e64 s[6:7], s14, v174
	v_cmp_le_u32_e64 s[10:11], s14, v175
	v_cmp_le_u32_e64 s[26:27], s14, v176
	v_addc_co_u32_e32 v0, vcc, 0, v0, vcc
	v_addc_co_u32_e64 v34, s[30:31], 0, v34, s[6:7]
	v_addc_co_u32_e64 v0, s[28:29], 0, v0, s[10:11]
	v_addc_co_u32_e64 v34, s[30:31], 0, v34, s[26:27]
	s_cmp_eq_u32 s32, 3
	s_cbranch_scc1 .Lsqa_red
	v_cmp_le_u32_e32 vcc, s14, v76
	v_cmp_le_u32_e64 s[6:7], s14, v78
	v_cmp_le_u32_e64 s[10:11], s14, v77
	v_cmp_le_u32_e64 s[26:27], s14, v79
	v_addc_co_u32_e32 v0, vcc, 0, v0, vcc
	v_addc_co_u32_e64 v34, s[30:31], 0, v34, s[6:7]
	v_addc_co_u32_e64 v0, s[28:29], 0, v0, s[10:11]
	v_addc_co_u32_e64 v34, s[30:31], 0, v34, s[26:27]
	v_cmp_le_u32_e32 vcc, s14, v80
	v_cmp_le_u32_e64 s[6:7], s14, v84
	v_cmp_le_u32_e64 s[10:11], s14, v81
	v_cmp_le_u32_e64 s[26:27], s14, v85
	v_addc_co_u32_e32 v0, vcc, 0, v0, vcc
	v_addc_co_u32_e64 v34, s[30:31], 0, v34, s[6:7]
	v_addc_co_u32_e64 v0, s[28:29], 0, v0, s[10:11]
	v_addc_co_u32_e64 v34, s[30:31], 0, v34, s[26:27]
	s_cmp_eq_u32 s32, 4
	s_cbranch_scc1 .Lsqa_red
	v_cmp_le_u32_e32 vcc, s14, v82
	v_cmp_le_u32_e64 s[6:7], s14, v86
	v_cmp_le_u32_e64 s[10:11], s14, v83
	v_cmp_le_u32_e64 s[26:27], s14, v87
	v_addc_co_u32_e32 v0, vcc, 0, v0, vcc
	v_addc_co_u32_e64 v34, s[30:31], 0, v34, s[6:7]
	v_addc_co_u32_e64 v0, s[28:29], 0, v0, s[10:11]
	v_addc_co_u32_e64 v34, s[30:31], 0, v34, s[26:27]
	v_cmp_le_u32_e32 vcc, s14, v89
	v_cmp_le_u32_e64 s[6:7], s14, v91
	v_cmp_le_u32_e64 s[10:11], s14, v90
	v_cmp_le_u32_e64 s[26:27], s14, v93
	v_addc_co_u32_e32 v0, vcc, 0, v0, vcc
	v_addc_co_u32_e64 v34, s[30:31], 0, v34, s[6:7]
	v_addc_co_u32_e64 v0, s[28:29], 0, v0, s[10:11]
	v_addc_co_u32_e64 v34, s[30:31], 0, v34, s[26:27]
	s_cmp_eq_u32 s32, 5
	s_cbranch_scc1 .Lsqa_red
	v_cmp_le_u32_e32 vcc, s14, v92
	v_cmp_le_u32_e64 s[6:7], s14, v95
	v_cmp_le_u32_e64 s[10:11], s14, v94
	v_cmp_le_u32_e64 s[26:27], s14, v96
	v_addc_co_u32_e32 v0, vcc, 0, v0, vcc
	v_addc_co_u32_e64 v34, s[30:31], 0, v34, s[6:7]
	v_addc_co_u32_e64 v0, s[28:29], 0, v0, s[10:11]
	v_addc_co_u32_e64 v34, s[30:31], 0, v34, s[26:27]
	v_cmp_le_u32_e32 vcc, s14, v97
	v_cmp_le_u32_e64 s[6:7], s14, v172
	v_cmp_le_u32_e64 s[10:11], s14, v171
	v_cmp_le_u32_e64 s[26:27], s14, v178
	v_addc_co_u32_e32 v0, vcc, 0, v0, vcc
	v_addc_co_u32_e64 v34, s[30:31], 0, v34, s[6:7]
	v_addc_co_u32_e64 v0, s[28:29], 0, v0, s[10:11]
	v_addc_co_u32_e64 v34, s[30:31], 0, v34, s[26:27]
	v_cmp_le_u32_e32 vcc, s14, v180
	v_cmp_le_u32_e64 s[6:7], s14, v183
	v_cmp_le_u32_e64 s[10:11], s14, v182
	v_cmp_le_u32_e64 s[26:27], s14, v184
	v_addc_co_u32_e32 v0, vcc, 0, v0, vcc
	v_addc_co_u32_e64 v34, s[30:31], 0, v34, s[6:7]
	v_addc_co_u32_e64 v0, s[28:29], 0, v0, s[10:11]
	v_addc_co_u32_e64 v34, s[30:31], 0, v34, s[26:27]
	v_cmp_le_u32_e32 vcc, s14, v186
	v_cmp_le_u32_e64 s[6:7], s14, v187
	v_cmp_le_u32_e64 s[10:11], s14, v188
	v_cmp_le_u32_e64 s[26:27], s14, v189
	v_addc_co_u32_e32 v0, vcc, 0, v0, vcc
	v_addc_co_u32_e64 v34, s[30:31], 0, v34, s[6:7]
	v_addc_co_u32_e64 v0, s[28:29], 0, v0, s[10:11]
	v_addc_co_u32_e64 v34, s[30:31], 0, v34, s[26:27]

; __device__ __forceinline__ int count_ge(const unsigned (&u)[64], unsigned cand, int nblk) {
;     int c0 = 0, c1 = 0;
;     const unsigned ts = __builtin_amdgcn_readfirstlane(cand);
; #pragma unroll
;     for (int B = 0; B < 2; ++B) {
;         if (B < nblk) {
; #pragma unroll
;             for (int i = 0; i < 32; i += 4) CNT4(c0, c1, ts, u[B * 32 + i], u[B * 32 + i + 1], u[B * 32 + i + 2], u[B * 32 + i + 3]);
;         }
;     }
;     return wave_isum(c0 + c1);
; }
.Lsqb_count:
	v_cmp_le_u32_e32 vcc, s14, v98
	v_cmp_le_u32_e64 s[6:7], s14, v107
	v_cmp_le_u32_e64 s[10:11], s14, v99
	v_cmp_le_u32_e64 s[26:27], s14, v108
	v_addc_co_u32_e64 v138, vcc, 0, 0, vcc
	v_addc_co_u32_e64 v140, s[30:31], 0, 0, s[6:7]
	v_addc_co_u32_e64 v138, s[28:29], 0, v138, s[10:11]
	v_addc_co_u32_e64 v140, s[30:31], 0, v140, s[26:27]
	v_cmp_le_u32_e32 vcc, s14, v109
	v_cmp_le_u32_e64 s[6:7], s14, v113
	v_cmp_le_u32_e64 s[10:11], s14, v110
	v_cmp_le_u32_e64 s[26:27], s14, v114
	v_addc_co_u32_e32 v138, vcc, 0, v138, vcc
	v_addc_co_u32_e64 v140, s[30:31], 0, v140, s[6:7]
	v_addc_co_u32_e64 v138, s[28:29], 0, v138, s[10:11]
	v_addc_co_u32_e64 v140, s[30:31], 0, v140, s[26:27]
	s_cmp_eq_u32 s32, 1
	s_cbranch_scc1 .Lsqb_red
	v_cmp_le_u32_e32 vcc, s14, v111
	v_cmp_le_u32_e64 s[6:7], s14, v115
	v_cmp_le_u32_e64 s[10:11], s14, v112
	v_cmp_le_u32_e64 s[26:27], s14, v116
	v_addc_co_u32_e32 v138, vcc, 0, v138, vcc
	v_addc_co_u32_e64 v140, s[30:31], 0, v140, s[6:7]
	v_addc_co_u32_e64 v138, s[28:29], 0, v138, s[10:11]
	v_addc_co_u32_e64 v140, s[30:31], 0, v140, s[26:27]
	v_cmp_le_u32_e32 vcc, s14, v117
	v_cmp_le_u32_e64 s[6:7], s14, v119
	v_cmp_le_u32_e64 s[10:11], s14, v118
	v_cmp_le_u32_e64 s[26:27], s14, v121
	v_addc_co_u32_e32 v138, vcc, 0, v138, vcc
	v_addc_co_u32_e64 v140, s[30:31], 0, v140, s[6:7]
	v_addc_co_u32_e64 v138, s[28:29], 0, v138, s[10:11]
	v_addc_co_u32_e64 v140, s[30:31], 0, v140, s[26:27]
	s_cmp_eq_u32 s32, 2
	s_cbranch_scc1 .Lsqb_red
	v_cmp_le_u32_e32 vcc, s14, v120
	v_cmp_le_u32_e64 s[6:7], s14, v123
	v_cmp_le_u32_e64 s[10:11], s14, v122
	v_cmp_le_u32_e64 s[26:27], s14, v124
	v_addc_co_u32_e32 v138, vcc, 0, v138, vcc
	v_addc_co_u32_e64 v140, s[30:31], 0, v140, s[6:7]
	v_addc_co_u32_e64 v138, s[28:29], 0, v138, s[10:11]
	v_addc_co_u32_e64 v140, s[30:31], 0, v140, s[26:27]
	v_cmp_le_u32_e32 vcc, s14, v125
	v_cmp_le_u32_e64 s[6:7], s14, v127
	v_cmp_le_u32_e64 s[10:11], s14, v126
	v_cmp_le_u32_e64 s[26:27], s14, v128
	v_addc_co_u32_e32 v138, vcc, 0, v138, vcc
	v_addc_co_u32_e64 v140, s[30:31], 0, v140, s[6:7]
	v_addc_co_u32_e64 v138, s[28:29], 0, v138, s[10:11]
	v_addc_co_u32_e64 v140, s[30:31], 0, v140, s[26:27]
	v_cmp_le_u32_e32 vcc, s14, v129
	v_cmp_le_u32_e64 s[6:7], s14, v131
	v_cmp_le_u32_e64 s[10:11], s14, v130
	v_cmp_le_u32_e64 s[26:27], s14, v132
	v_addc_co_u32_e32 v138, vcc, 0, v138, vcc
	v_addc_co_u32_e64 v140, s[30:31], 0, v140, s[6:7]
	v_addc_co_u32_e64 v138, s[28:29], 0, v138, s[10:11]
	v_addc_co_u32_e64 v140, s[30:31], 0, v140, s[26:27]
	v_cmp_le_u32_e32 vcc, s14, v133
	v_cmp_le_u32_e64 s[6:7], s14, v134
	v_cmp_le_u32_e64 s[10:11], s14, v136
	v_cmp_le_u32_e64 s[26:27], s14, v137
	v_addc_co_u32_e32 v138, vcc, 0, v138, vcc
	v_addc_co_u32_e64 v140, s[30:31], 0, v140, s[6:7]
	v_addc_co_u32_e64 v138, s[28:29], 0, v138, s[10:11]
	v_addc_co_u32_e64 v140, s[30:31], 0, v140, s[26:27]
	s_cmp_eq_u32 s32, 3
	s_cbranch_scc1 .Lsqb_red
	v_cmp_le_u32_e32 vcc, s14, v46
	v_cmp_le_u32_e64 s[6:7], s14, v48
	v_cmp_le_u32_e64 s[10:11], s14, v47
	v_cmp_le_u32_e64 s[26:27], s14, v49
	v_addc_co_u32_e32 v138, vcc, 0, v138, vcc
	v_addc_co_u32_e64 v140, s[30:31], 0, v140, s[6:7]
	v_addc_co_u32_e64 v138, s[28:29], 0, v138, s[10:11]
	v_addc_co_u32_e64 v140, s[30:31], 0, v140, s[26:27]
	v_cmp_le_u32_e32 vcc, s14, v42
	v_cmp_le_u32_e64 s[6:7], s14, v50
	v_cmp_le_u32_e64 s[10:11], s14, v43
	v_cmp_le_u32_e64 s[26:27], s14, v44
	v_addc_co_u32_e32 v138, vcc, 0, v138, vcc
	v_addc_co_u32_e64 v140, s[30:31], 0, v140, s[6:7]
	v_addc_co_u32_e64 v138, s[28:29], 0, v138, s[10:11]
	v_addc_co_u32_e64 v140, s[30:31], 0, v140, s[26:27]
	s_cmp_eq_u32 s32, 4
	s_cbranch_scc1 .Lsqb_red
	v_cmp_le_u32_e32 vcc, s14, v38
	v_cmp_le_u32_e64 s[6:7], s14, v45
	v_cmp_le_u32_e64 s[10:11], s14, v39
	v_cmp_le_u32_e64 s[26:27], s14, v40
	v_addc_co_u32_e32 v138, vcc, 0, v138, vcc
	v_addc_co_u32_e64 v140, s[30:31], 0, v140, s[6:7]
	v_addc_co_u32_e64 v138, s[28:29], 0, v138, s[10:11]
	v_addc_co_u32_e64 v140, s[30:31], 0, v140, s[26:27]
	v_cmp_le_u32_e32 vcc, s14, v41
	v_cmp_le_u32_e64 s[6:7], s14, v52
	v_cmp_le_u32_e64 s[10:11], s14, v51
	v_cmp_le_u32_e64 s[26:27], s14, v54
	v_addc_co_u32_e32 v138, vcc, 0, v138, vcc
	v_addc_co_u32_e64 v140, s[30:31], 0, v140, s[6:7]
	v_addc_co_u32_e64 v138, s[28:29], 0, v138, s[10:11]
	v_addc_co_u32_e64 v140, s[30:31], 0, v140, s[26:27]
	s_cmp_eq_u32 s32, 5
	s_cbranch_scc1 .Lsqb_red
	v_cmp_le_u32_e32 vcc, s14, v53
	v_cmp_le_u32_e64 s[6:7], s14, v56
	v_cmp_le_u32_e64 s[10:11], s14, v55
	v_cmp_le_u32_e64 s[26:27], s14, v57
	v_addc_co_u32_e32 v138, vcc, 0, v138, vcc
	v_addc_co_u32_e64 v140, s[30:31], 0, v140, s[6:7]
	v_addc_co_u32_e64 v138, s[28:29], 0, v138, s[10:11]
	v_addc_co_u32_e64 v140, s[30:31], 0, v140, s[26:27]
	v_cmp_le_u32_e32 vcc, s14, v58
	v_cmp_le_u32_e64 s[6:7], s14, v60
	v_cmp_le_u32_e64 s[10:11], s14, v59
	v_cmp_le_u32_e64 s[26:27], s14, v61
	v_addc_co_u32_e32 v138, vcc, 0, v138, vcc
	v_addc_co_u32_e64 v140, s[30:31], 0, v140, s[6:7]
	v_addc_co_u32_e64 v138, s[28:29], 0, v138, s[10:11]
	v_addc_co_u32_e64 v140, s[30:31], 0, v140, s[26:27]
	v_cmp_le_u32_e32 vcc, s14, v62
	v_cmp_le_u32_e64 s[6:7], s14, v64
	v_cmp_le_u32_e64 s[10:11], s14, v63
	v_cmp_le_u32_e64 s[26:27], s14, v65
	v_addc_co_u32_e32 v138, vcc, 0, v138, vcc
	v_addc_co_u32_e64 v140, s[30:31], 0, v140, s[6:7]
	v_addc_co_u32_e64 v138, s[28:29], 0, v138, s[10:11]
	v_addc_co_u32_e64 v140, s[30:31], 0, v140, s[26:27]
	v_cmp_le_u32_e32 vcc, s14, v72
	v_cmp_le_u32_e64 s[6:7], s14, v73
	v_cmp_le_u32_e64 s[10:11], s14, v74
	v_cmp_le_u32_e64 s[26:27], s14, v75
	v_addc_co_u32_e32 v138, vcc, 0, v138, vcc
	v_addc_co_u32_e64 v140, s[30:31], 0, v140, s[6:7]
	v_addc_co_u32_e64 v138, s[28:29], 0, v138, s[10:11]
	v_addc_co_u32_e64 v140, s[30:31], 0, v140, s[26:27]
